# baseline (speedup 1.0000x reference)
; __device__ __forceinline__ int otid() { int t = threadIdx.x; asm volatile("" : "+v"(t)); return t; }
; __device__ __forceinline__ int uni(int x) { return __builtin_amdgcn_readfirstlane(x); }
; #define ATT_LOAD(kt) do { kr[0] = *(const u32x4*)(kbase + (size_t)((kt) * 64 + krow) * NPROJ + kcs); kr[1] = *(const u32x4*)(kbase + (size_t)((kt) * 64 + 32 + krow) * NPROJ + kcs); \
;         vr[0] = *(const u32x4*)(vtb + (size_t)vd * 4096 + (kt) * 64 + vsg); vr[1] = *(const u32x4*)(vtb + (size_t)(64 + vd) * 4096 + (kt) * 64 + vsg); } while (0)
; __device__ __forceinline__ void attn_prompt_item(unsigned char* lds, const Params& p, int item, bool dry) {
;     ...
;     const int cp = item & 31, h = (item >> 5) & 7, b = item >> 8, c0 = 2 * cp;
;     const int tid = otid(), wave = uni(tid >> 6), lane = tid & 63, li = lane & 15, fq = lane >> 4;
;     const int ci = c0 + (wave >> 2), rb = wave & 3;
;     float* tab = (float*)(lds + TAB_OFF);
;     __syncthreads();
;     if (tid < 257) tab[tid] = p.in[10][h * 257 + tid];
;     const int tq_row = ci * 64 + 16 * rb + li;
;     bf16_t* qrow = P + (size_t)(b * TP + tq_row) * NPROJ + C_QB + h * 128;
;     bf16x8 qf[4];
; #pragma unroll
;     for (int ks = 0; ks < 4; ++ks) qf[ks] = *(const bf16x8*)(qrow + 32 * ks + 8 * fq);
;     f32x4 o[8];
; #pragma unroll
;     for (int db = 0; db < 8; ++db) o[db] = (f32x4){0.f, 0.f, 0.f, 0.f};
;     float m = -1e30f, l = 0.f;
;     const int kt0 = (c0 - 8) > 0 ? (c0 - 8) : 0, kt1 = c0 + 1;
;     const bf16_t* kbase = P + (size_t)(b * TP) * NPROJ + C_KB + h * 128;
;     const bf16_t* vtb = (const bf16_t*)((const unsigned char*)p.out + OS_VTB) + (size_t)((b * 8 + h) * 128) * 4096;
;     const int krow = tid >> 4, kcs = (tid & 15) * 8, vd = tid >> 3, vsg = (tid & 7) * 8;
;     u32x4 kr[2], vr[2];
;     ...
;     ATT_LOAD(kt0);
.LBB0_815:
	s_or_b64 exec, exec, s[0:1]
	s_lshl_b32 s0, s73, 1
	s_and_b32 s2, s0, 62
	s_bfe_u32 s0, s29, 0x50001
	s_ashr_i32 s8, s5, 8
	s_lshl_b32 s1, s0, 1
	s_add_i32 s3, s8, s2
	s_min_u32 s9, s1, 8
	s_lshl_b32 s10, s0, 7
	s_lshl_b32 s0, s73, 3
	s_lshr_b32 s1, s5, 2
	s_and_b32 s12, s0, 0x700
	s_lshl_b32 s0, s3, 6
	s_and_b32 s14, s1, 48
	s_ashr_i32 s6, s73, 8
	v_and_b32_e32 v38, 15, v16
	s_or_b32 s0, s0, s14
	v_readlane_b32 s16, v251, 50
	s_waitcnt vmcnt(3)
	v_or_b32_e32 v0, s0, v38
	s_lshl_b32 s5, s6, 12
	v_readlane_b32 s17, v251, 51
	v_add_u32_e32 v2, s5, v0
	s_lshl_b32 s11, s9, 6
	v_mov_b64_e32 v[0:1], s[16:17]
	v_mad_i64_i32 v[0:1], s[0:1], v2, s95, v[0:1]
	s_sub_i32 s13, s10, s11
	s_lshl_b32 s0, s4, 7
	s_lshl_b32 s60, s4, 8
	s_mul_i32 s15, s6, 0x3200000
	s_mul_hi_i32 s1, s5, 0x3200
	s_add_u32 s4, s16, s15
	s_addc_u32 s5, s17, s1
	s_add_u32 s4, s4, s60
	s_addc_u32 s5, s5, 0
	s_add_u32 s4, s4, 0x2000
	s_addc_u32 s5, s5, 0
	s_lshl_b32 s6, s6, 10
	s_or_b32 s6, s0, s6
	s_ashr_i32 s7, s6, 31
	s_lshl_b64 s[6:7], s[6:7], 13
	v_ashrrev_i32_e32 v32, 3, v16
	s_add_u32 s6, s27, s6
	v_lshlrev_b32_e32 v17, 3, v16
	v_ashrrev_i32_e32 v33, 31, v32
	v_bfe_u32 v39, v16, 4, 2
	v_lshl_add_u64 v[0:1], v[0:1], 0, s[60:61]
	s_mov_b64 s[18:19], 0x1800
	s_addc_u32 s7, s59, s7
	v_ashrrev_i32_e32 v40, 4, v16
	v_and_b32_e32 v28, 0x78, v17
	v_and_b32_e32 v18, 56, v17
	v_lshlrev_b64 v[16:17], 13, v[32:33]
	v_sub_u32_e64 v33, s2, 8 clamp
	v_lshl_add_u64 v[78:79], v[0:1], 0, s[18:19]
	v_lshlrev_b32_e32 v76, 4, v39
	v_lshl_add_u64 v[34:35], s[6:7], 0, v[16:17]
	s_mov_b64 s[6:7], 0x80000
	v_lshl_add_u32 v29, v33, 6, v40
	s_waitcnt vmcnt(0)
	v_lshl_add_u64 v[12:13], v[78:79], 0, v[76:77]
	v_lshl_add_u64 v[36:37], v[34:35], 0, s[6:7]
	v_lshlrev_b32_e32 v16, 7, v33
	v_mov_b32_e32 v17, v77
	v_add_u32_e32 v26, 32, v29
	v_mov_b64_e32 v[24:25], s[4:5]
	global_load_dwordx4 v[0:3], v[12:13], off
	global_load_dwordx4 v[4:7], v[12:13], off offset:64
	global_load_dwordx4 v[8:11], v[12:13], off offset:128
	s_nop 0
	global_load_dwordx4 v[12:15], v[12:13], off offset:192
	v_lshlrev_b32_e32 v80, 1, v18
	v_mov_b32_e32 v81, v77
	v_lshl_add_u64 v[18:19], v[36:37], 0, v[16:17]
	v_lshl_add_u64 v[16:17], v[34:35], 0, v[16:17]
	v_mad_i64_i32 v[26:27], s[4:5], v26, s95, v[24:25]
	v_lshlrev_b32_e32 v82, 1, v28
	v_mov_b32_e32 v83, v77
	v_mad_i64_i32 v[24:25], s[4:5], v29, s95, v[24:25]
	v_lshl_add_u64 v[18:19], v[18:19], 0, v[80:81]
	v_lshl_add_u64 v[16:17], v[16:17], 0, v[80:81]
	v_lshl_add_u64 v[26:27], v[26:27], 0, v[82:83]
	v_lshl_add_u64 v[28:29], v[24:25], 0, v[82:83]
	global_load_dwordx4 v[20:23], v[18:19], off
	s_nop 0
	global_load_dwordx4 v[16:19], v[16:17], off
	s_nop 0
	global_load_dwordx4 v[24:27], v[26:27], off
	s_nop 0
	global_load_dwordx4 v[28:31], v[28:29], off
	s_add_i32 s8, s8, s9
	s_lshl_b32 s0, s8, 6
	s_or_b32 s0, s0, s14
	s_sub_i32 s0, s0, 51
	v_lshl_add_u64 v[84:85], v[34:35], 0, v[80:81]
	v_lshl_add_u64 v[86:87], v[36:37], 0, v[80:81]
	v_mul_lo_u32 v83, v32, s94
	v_lshlrev_b32_e32 v81, 2, v39
	v_add_u32_e32 v32, s0, v38
	v_sub_u32_e32 v95, v32, v81
	v_add_u32_e32 v32, s10, v40
	s_or_b32 s0, s15, s12
	v_readfirstlane_b32 s4, v33
	v_subrev_u32_e32 v37, s11, v32
	v_mov_b64_e32 v[32:33], s[0:1]
	v_mul_u32_u24_e32 v93, 0x110, v38
	v_mul_u32_u24_e32 v36, 0x48, v38
	v_mad_i64_i32 v[34:35], s[0:1], v37, s95, v[32:33]
	v_lshlrev_b32_e32 v38, 4, v38
	v_or_b32_e32 v34, v34, v38
	v_lshl_add_u64 v[88:89], s[38:39], 0, v[34:35]
	v_add_u32_e32 v34, 0x60, v37
	v_mad_i64_i32 v[32:33], s[0:1], v34, s95, v[32:33]
	v_or_b32_e32 v32, v32, v38
	v_mov_b32_e32 v97, 0
	v_add_u32_e32 v92, 0x2400, v83
	s_add_i32 s5, s3, -8
	v_mul_lo_u32 v94, v40, s96
	v_lshl_add_u64 v[90:91], s[64:65], 0, v[32:33]
	v_mov_b32_e32 v98, 0xf149f2ca
	v_lshlrev_b32_e32 v96, 1, v36
	s_mov_b32 s60, s13
	v_mov_b32_e32 v32, 0
	v_mov_b32_e32 v33, v97
	v_mov_b32_e32 v34, v97
	v_mov_b32_e32 v35, v97
	v_mov_b32_e32 v36, 0
	v_mov_b32_e32 v37, v97
	v_mov_b32_e32 v38, v97
	v_mov_b32_e32 v39, v97
	v_mov_b32_e32 v40, 0
	v_mov_b32_e32 v41, v97
	v_mov_b32_e32 v42, v97
	v_mov_b32_e32 v43, v97
	v_mov_b32_e32 v44, 0
	v_mov_b32_e32 v45, v97
	v_mov_b32_e32 v46, v97
	v_mov_b32_e32 v47, v97
	v_mov_b32_e32 v48, 0
	v_mov_b32_e32 v49, v97
	v_mov_b32_e32 v50, v97
	v_mov_b32_e32 v51, v97
	v_mov_b32_e32 v52, 0
	v_mov_b32_e32 v53, v97
	v_mov_b32_e32 v54, v97
	v_mov_b32_e32 v55, v97
	v_mov_b32_e32 v56, 0
	v_mov_b32_e32 v57, v97
	v_mov_b32_e32 v58, v97
	v_mov_b32_e32 v59, v97
	v_mov_b32_e32 v60, 0
	v_mov_b32_e32 v61, v97
	v_mov_b32_e32 v62, v97
	v_mov_b32_e32 v63, v97
	v_mov_b32_e32 v204, s60
	v_mov_b32_e32 v205, 0
	v_lshl_add_u64 v[208:209], v[204:205], 1, v[84:85]
	v_lshl_add_u64 v[210:211], v[204:205], 1, v[86:87]
	global_load_dword v200, v[88:89], off
	global_load_dword v201, v[90:91], off
	global_load_dword v202, v[208:209], off offset:128
	global_load_dword v203, v[210:211], off offset:128
	s_branch .LBB0_817

; #define ATT_LOAD(kt) do { kr[0] = *(const u32x4*)(kbase + (size_t)((kt) * 64 + krow) * NPROJ + kcs); kr[1] = *(const u32x4*)(kbase + (size_t)((kt) * 64 + 32 + krow) * NPROJ + kcs); \
;         vr[0] = *(const u32x4*)(vtb + (size_t)vd * 4096 + (kt) * 64 + vsg); vr[1] = *(const u32x4*)(vtb + (size_t)(64 + vd) * 4096 + (kt) * 64 + vsg); } while (0)
; __device__ __forceinline__ void attn_prompt_item(unsigned char* lds, const Params& p, int item, bool dry) {
;     ...
;     for (int kt = kt0; kt <= kt1; ++kt) {
;         unsigned char* bufp = lds + KL_OFF + ((kt - kt0) & 1) * KV_BUF;
;         bf16_t* Kl = (bf16_t*)bufp; bf16_t* VTl = (bf16_t*)(bufp + 17408);
;         *(u32x4*)(Kl + krow * 136 + kcs) = kr[0]; *(u32x4*)(Kl + (32 + krow) * 136 + kcs) = kr[1];
;         *(u32x4*)(VTl + vd * 72 + vsg) = vr[0]; *(u32x4*)(VTl + (64 + vd) * 72 + vsg) = vr[1];
;         if (kt < kt1) ATT_LOAD(kt + 1);
;         __syncthreads();
.LBB0_817:
	s_bitcmp1_b32 s4, 0
	s_cselect_b32 s0, 0x8c00, 0
	s_add_i32 s6, s0, 0
	v_add3_u32 v64, s6, v94, v82
	s_cmp_gt_u32 s4, s2
	s_waitcnt vmcnt(4)
	ds_write_b128 v64, v[28:31] offset:1280
	ds_write_b128 v64, v[24:27] offset:9984
	v_add3_u32 v64, s6, v83, v80
	s_cselect_b64 s[0:1], -1, 0
	ds_write_b128 v64, v[16:19] offset:18688
	v_add3_u32 v64, s6, v92, v80
	s_and_b64 vcc, exec, s[0:1]
	ds_write_b128 v64, v[20:23] offset:18688
	s_cbranch_vccnz .LBB0_819
	s_lshl_b64 s[8:9], s[60:61], 1
	v_lshl_add_u64 v[16:17], v[84:85], 0, s[8:9]
	v_lshl_add_u64 v[20:21], v[86:87], 0, s[8:9]
	global_load_dwordx4 v[28:31], v[88:89], off
	global_load_dwordx4 v[24:27], v[90:91], off
	s_nop 0
	global_load_dwordx4 v[16:19], v[16:17], off offset:128
	s_nop 0
	global_load_dwordx4 v[20:23], v[20:21], off offset:128
	v_lshl_add_u64 v[204:205], v[88:89], 0, s[68:69]
	v_lshl_add_u64 v[206:207], v[90:91], 0, s[68:69]
	v_lshl_add_u64 v[208:209], v[84:85], 0, s[8:9]
	v_lshl_add_u64 v[210:211], v[86:87], 0, s[8:9]
	global_load_dword v200, v[204:205], off
	global_load_dword v201, v[206:207], off
	global_load_dword v202, v[208:209], off offset:256
	global_load_dword v203, v[210:211], off offset:256
